# stack11 + scan2: one workgroup barrier per step (SH/SL state images double-buffered, barrier between MFMA reads and split stores removed)
# speedup vs baseline: 1.0018x; 1.0018x over previous
.LBB0_664:
	s_and_b64 vcc, exec, s[8:9]
	s_cbranch_vccnz .LBB0_666
	s_nop 7
	v_cvt_pk_bf16_f32 v0, v36, v36
	v_lshlrev_b32_e32 v55, 16, v0
	v_sub_f32_e32 v55, v36, v55
	ds_write_b16 v70, v0 offset:31232
	v_cvt_pk_bf16_f32 v0, v55, s0
	ds_write_b16 v70, v0 offset:33536
	v_cvt_pk_bf16_f32 v0, v37, v37
	v_lshlrev_b32_e32 v55, 16, v0
	v_sub_f32_e32 v55, v37, v55
	ds_write_b16 v70, v0 offset:31376
	v_cvt_pk_bf16_f32 v0, v55, s0
	ds_write_b16 v70, v0 offset:33680
	v_cvt_pk_bf16_f32 v0, v38, v38
	v_lshlrev_b32_e32 v55, 16, v0
	v_sub_f32_e32 v55, v38, v55
	ds_write_b16 v70, v0 offset:31520
	v_cvt_pk_bf16_f32 v0, v55, s0
	ds_write_b16 v70, v0 offset:33824
	v_cvt_pk_bf16_f32 v0, v39, v39
	v_lshlrev_b32_e32 v55, 16, v0
	v_sub_f32_e32 v55, v39, v55
	ds_write_b16 v71, v0 offset:31232
	v_cvt_pk_bf16_f32 v0, v55, s0
	ds_write_b16 v71, v0 offset:33536

.LBB0_670:
	s_add_i32 s11, s27, s36
	s_add_i32 s30, s11, -7
	s_ashr_i32 s31, s30, 31
	s_lshl_b64 s[30:31], s[30:31], 13
	v_lshl_add_u64 v[102:103], v[62:63], 0, s[30:31]
	v_cvt_pk_bf16_f32 v98, v36, s0
	v_cvt_pk_bf16_f32 v99, v37, s0
	v_cvt_pk_bf16_f32 v100, v38, s0
	v_cvt_pk_bf16_f32 v101, v39, s0
	v_add_u32_e32 v0, v69, v72
	ds_read2st64_b32 v[36:37], v0 offset0:88 offset1:89
	ds_read_b32 v38, v0 offset:23040
	v_add_u32_e32 v0, v69, v73
	ds_read_b32 v39, v0 offset:22528
	ds_read_b128 v[74:77], v67 offset:9216
	ds_read_b128 v[78:81], v68 offset:31232
	ds_read_b128 v[82:85], v68 offset:33536
	ds_read_b128 v[86:89], v67 offset:9280
	ds_read_b128 v[90:93], v68 offset:31296
	ds_read_b128 v[94:97], v68 offset:33600
	global_store_short v[102:103], v98, off
	global_store_short v[102:103], v99, off offset:128
	s_waitcnt lgkmcnt(4)
	v_mfma_f32_16x16x32_bf16 v[36:39], v[78:81], v[74:77], v[36:39]
	global_store_short v[102:103], v100, off offset:256
	s_waitcnt lgkmcnt(3)
	v_mfma_f32_16x16x32_bf16 v[36:39], v[82:85], v[74:77], v[36:39]
	global_store_short v[102:103], v101, off offset:384
	s_waitcnt lgkmcnt(1)
	v_mfma_f32_16x16x32_bf16 v[36:39], v[90:93], v[86:89], v[36:39]
	s_waitcnt lgkmcnt(0)
	v_mfma_f32_16x16x32_bf16 v[36:39], v[94:97], v[86:89], v[36:39]
.LBB0_671:
	s_and_b64 vcc, exec, s[8:9]
	s_cbranch_vccnz .LBB0_673
	s_nop 7
	v_cvt_pk_bf16_f32 v0, v36, v36
	v_lshlrev_b32_e32 v55, 16, v0
	v_sub_f32_e32 v55, v36, v55
	ds_write_b16 v70, v0 offset:26624
	v_cvt_pk_bf16_f32 v0, v55, s0
	ds_write_b16 v70, v0 offset:28928
	v_cvt_pk_bf16_f32 v0, v37, v37
	v_lshlrev_b32_e32 v55, 16, v0
	v_sub_f32_e32 v55, v37, v55
	ds_write_b16 v70, v0 offset:26768
	v_cvt_pk_bf16_f32 v0, v55, s0
	ds_write_b16 v70, v0 offset:29072
	v_cvt_pk_bf16_f32 v0, v38, v38
	v_lshlrev_b32_e32 v55, 16, v0
	v_sub_f32_e32 v55, v38, v55
	ds_write_b16 v70, v0 offset:26912
	v_cvt_pk_bf16_f32 v0, v55, s0
	ds_write_b16 v70, v0 offset:29216
	v_cvt_pk_bf16_f32 v0, v39, v39
	v_lshlrev_b32_e32 v55, 16, v0
	v_sub_f32_e32 v55, v39, v55
	ds_write_b16 v71, v0 offset:26624
	v_cvt_pk_bf16_f32 v0, v55, s0
	ds_write_b16 v71, v0 offset:28928

.LBB0_684:
	s_add_i32 s11, s27, s36
	s_add_i32 s28, s11, -5
	s_ashr_i32 s29, s28, 31
	s_lshl_b64 s[28:29], s[28:29], 13
	v_lshl_add_u64 v[102:103], v[62:63], 0, s[28:29]
	v_cvt_pk_bf16_f32 v98, v36, s0
	v_cvt_pk_bf16_f32 v99, v37, s0
	v_cvt_pk_bf16_f32 v100, v38, s0
	v_cvt_pk_bf16_f32 v101, v39, s0
	v_add_u32_e32 v0, v69, v72
	ds_read2st64_b32 v[36:37], v0 offset0:88 offset1:89
	ds_read_b32 v38, v0 offset:23040
	v_add_u32_e32 v0, v69, v73
	ds_read_b32 v39, v0 offset:22528
	ds_read_b128 v[74:77], v67 offset:9216
	ds_read_b128 v[78:81], v68 offset:31232
	ds_read_b128 v[82:85], v68 offset:33536
	ds_read_b128 v[86:89], v67 offset:9280
	ds_read_b128 v[90:93], v68 offset:31296
	ds_read_b128 v[94:97], v68 offset:33600
	global_store_short v[102:103], v98, off
	global_store_short v[102:103], v99, off offset:128
	s_waitcnt lgkmcnt(4)
	v_mfma_f32_16x16x32_bf16 v[36:39], v[78:81], v[74:77], v[36:39]
	global_store_short v[102:103], v100, off offset:256
	s_waitcnt lgkmcnt(3)
	v_mfma_f32_16x16x32_bf16 v[36:39], v[82:85], v[74:77], v[36:39]
	global_store_short v[102:103], v101, off offset:384
	s_waitcnt lgkmcnt(1)
	v_mfma_f32_16x16x32_bf16 v[36:39], v[90:93], v[86:89], v[36:39]
	s_waitcnt lgkmcnt(0)
	v_mfma_f32_16x16x32_bf16 v[36:39], v[94:97], v[86:89], v[36:39]
